# hand-written GLU epilogue: gate loads first, sigmoid products computed while they are in flight
# baseline (speedup 1.0000x reference)
.LBB0_178:
	s_andn2_b64 vcc, exec, s[38:39]
	s_cbranch_vccnz .LBB0_221
	v_add_u32_e32 v188, 0x80, v180
	v_add_u32_e32 v186, 0x90, v180
	v_add_u32_e32 v184, 0xa0, v180
	v_add_u32_e32 v182, 0xb0, v180
	s_mov_b64 s[38:39], -1
	s_cmp_gt_i32 s81, 0
	v_ashrrev_i32_e32 v181, 31, v180
	v_or_b32_e32 v194, 16, v180
	v_or_b32_e32 v192, 32, v180
	v_or_b32_e32 v190, 48, v180
	v_ashrrev_i32_e32 v189, 31, v188
	v_ashrrev_i32_e32 v187, 31, v186
	v_ashrrev_i32_e32 v185, 31, v184
	v_ashrrev_i32_e32 v183, 31, v182
	s_cbranch_scc0 .LBB0_181
	s_mov_b32 s74, 0xbfb8aa3b
	s_mov_b32 s88, 1.0
	s_lshl_b32 s38, s54, 8
	v_lshl_add_u32 v196, v172, 1, s38
	v_lshl_add_u32 v198, v180, 12, v196
	v_mov_b32_e32 v199, 0
	v_lshl_add_u32 v216, v180, 11, v196
	v_mov_b32_e32 v217, 0
	v_lshl_add_u64 v[198:199], s[64:65], 0, v[198:199]
	v_lshl_add_u64 v[216:217], s[18:19], 0, v[216:217]
	s_mov_b64 s[56:57], 0x10000
	s_mov_b64 s[38:39], 0x50000
	global_load_dwordx4 v[130:133], v[198:199], off offset:2048
	v_lshl_add_u64 v[198:199], v[198:199], 0, s[56:57]
	global_load_dwordx4 v[134:137], v[198:199], off offset:2048
	v_lshl_add_u64 v[198:199], v[198:199], 0, s[56:57]
	global_load_dwordx4 v[138:141], v[198:199], off offset:2048
	v_lshl_add_u64 v[198:199], v[198:199], 0, s[56:57]
	global_load_dwordx4 v[142:145], v[198:199], off offset:2048
	v_lshl_add_u64 v[198:199], v[198:199], 0, s[38:39]
	global_load_dwordx4 v[146:149], v[198:199], off offset:2048
	v_lshl_add_u64 v[198:199], v[198:199], 0, s[56:57]
	global_load_dwordx4 v[150:153], v[198:199], off offset:2048
	v_lshl_add_u64 v[198:199], v[198:199], 0, s[56:57]
	global_load_dwordx4 v[154:157], v[198:199], off offset:2048
	v_lshl_add_u64 v[198:199], v[198:199], 0, s[56:57]
	global_load_dwordx4 v[158:161], v[198:199], off offset:2048
	v_pk_mul_f32 v[200:201], v[118:119], s[74:75] op_sel_hi:[1,0]
	v_pk_mul_f32 v[202:203], v[120:121], s[74:75] op_sel_hi:[1,0]
	v_pk_mul_f32 v[204:205], v[114:115], s[74:75] op_sel_hi:[1,0]
	v_pk_mul_f32 v[206:207], v[116:117], s[74:75] op_sel_hi:[1,0]
	v_pk_mul_f32 v[208:209], v[102:103], s[74:75] op_sel_hi:[1,0]
	v_pk_mul_f32 v[210:211], v[104:105], s[74:75] op_sel_hi:[1,0]
	v_pk_mul_f32 v[212:213], v[98:99], s[74:75] op_sel_hi:[1,0]
	v_pk_mul_f32 v[214:215], v[100:101], s[74:75] op_sel_hi:[1,0]
	v_exp_f32_e32 v200, v200
	v_exp_f32_e32 v201, v201
	v_exp_f32_e32 v202, v202
	v_exp_f32_e32 v203, v203
	v_exp_f32_e32 v204, v204
	v_exp_f32_e32 v205, v205
	v_exp_f32_e32 v206, v206
	v_exp_f32_e32 v207, v207
	v_exp_f32_e32 v208, v208
	v_exp_f32_e32 v209, v209
	v_exp_f32_e32 v210, v210
	v_exp_f32_e32 v211, v211
	v_exp_f32_e32 v212, v212
	v_exp_f32_e32 v213, v213
	v_exp_f32_e32 v214, v214
	v_exp_f32_e32 v215, v215
	v_pk_add_f32 v[200:201], v[200:201], s[88:89] op_sel_hi:[1,0]
	v_pk_add_f32 v[202:203], v[202:203], s[88:89] op_sel_hi:[1,0]
	v_pk_add_f32 v[204:205], v[204:205], s[88:89] op_sel_hi:[1,0]
	v_pk_add_f32 v[206:207], v[206:207], s[88:89] op_sel_hi:[1,0]
	v_pk_add_f32 v[208:209], v[208:209], s[88:89] op_sel_hi:[1,0]
	v_pk_add_f32 v[210:211], v[210:211], s[88:89] op_sel_hi:[1,0]
	v_pk_add_f32 v[212:213], v[212:213], s[88:89] op_sel_hi:[1,0]
	v_pk_add_f32 v[214:215], v[214:215], s[88:89] op_sel_hi:[1,0]
	v_rcp_f32_e32 v200, v200
	v_rcp_f32_e32 v201, v201
	v_rcp_f32_e32 v202, v202
	v_rcp_f32_e32 v203, v203
	v_rcp_f32_e32 v204, v204
	v_rcp_f32_e32 v205, v205
	v_rcp_f32_e32 v206, v206
	v_rcp_f32_e32 v207, v207
	v_rcp_f32_e32 v208, v208
	v_rcp_f32_e32 v209, v209
	v_rcp_f32_e32 v210, v210
	v_rcp_f32_e32 v211, v211
	v_rcp_f32_e32 v212, v212
	v_rcp_f32_e32 v213, v213
	v_rcp_f32_e32 v214, v214
	v_rcp_f32_e32 v215, v215
	v_pk_mul_f32 v[126:127], v[126:127], v[200:201]
	v_pk_mul_f32 v[128:129], v[128:129], v[202:203]
	v_pk_mul_f32 v[122:123], v[122:123], v[204:205]
	v_pk_mul_f32 v[124:125], v[124:125], v[206:207]
	v_pk_mul_f32 v[110:111], v[110:111], v[208:209]
	v_pk_mul_f32 v[112:113], v[112:113], v[210:211]
	v_pk_mul_f32 v[106:107], v[106:107], v[212:213]
	v_pk_mul_f32 v[108:109], v[108:109], v[214:215]
	v_pk_mul_f32 v[200:201], v[86:87], s[74:75] op_sel_hi:[1,0]
	v_pk_mul_f32 v[202:203], v[88:89], s[74:75] op_sel_hi:[1,0]
	v_pk_mul_f32 v[204:205], v[82:83], s[74:75] op_sel_hi:[1,0]
	v_pk_mul_f32 v[206:207], v[84:85], s[74:75] op_sel_hi:[1,0]
	v_pk_mul_f32 v[208:209], v[70:71], s[74:75] op_sel_hi:[1,0]
	v_pk_mul_f32 v[210:211], v[72:73], s[74:75] op_sel_hi:[1,0]
	v_pk_mul_f32 v[212:213], v[66:67], s[74:75] op_sel_hi:[1,0]
	v_pk_mul_f32 v[214:215], v[68:69], s[74:75] op_sel_hi:[1,0]
	v_exp_f32_e32 v200, v200
	v_exp_f32_e32 v201, v201
	v_exp_f32_e32 v202, v202
	v_exp_f32_e32 v203, v203
	v_exp_f32_e32 v204, v204
	v_exp_f32_e32 v205, v205
	v_exp_f32_e32 v206, v206
	v_exp_f32_e32 v207, v207
	v_exp_f32_e32 v208, v208
	v_exp_f32_e32 v209, v209
	v_exp_f32_e32 v210, v210
	v_exp_f32_e32 v211, v211
	v_exp_f32_e32 v212, v212
	v_exp_f32_e32 v213, v213
	v_exp_f32_e32 v214, v214
	v_exp_f32_e32 v215, v215
	v_pk_add_f32 v[200:201], v[200:201], s[88:89] op_sel_hi:[1,0]
	v_pk_add_f32 v[202:203], v[202:203], s[88:89] op_sel_hi:[1,0]
	v_pk_add_f32 v[204:205], v[204:205], s[88:89] op_sel_hi:[1,0]
	v_pk_add_f32 v[206:207], v[206:207], s[88:89] op_sel_hi:[1,0]
	v_pk_add_f32 v[208:209], v[208:209], s[88:89] op_sel_hi:[1,0]
	v_pk_add_f32 v[210:211], v[210:211], s[88:89] op_sel_hi:[1,0]
	v_pk_add_f32 v[212:213], v[212:213], s[88:89] op_sel_hi:[1,0]
	v_pk_add_f32 v[214:215], v[214:215], s[88:89] op_sel_hi:[1,0]
	v_rcp_f32_e32 v200, v200
	v_rcp_f32_e32 v201, v201
	v_rcp_f32_e32 v202, v202
	v_rcp_f32_e32 v203, v203
	v_rcp_f32_e32 v204, v204
	v_rcp_f32_e32 v205, v205
	v_rcp_f32_e32 v206, v206
	v_rcp_f32_e32 v207, v207
	v_rcp_f32_e32 v208, v208
	v_rcp_f32_e32 v209, v209
	v_rcp_f32_e32 v210, v210
	v_rcp_f32_e32 v211, v211
	v_rcp_f32_e32 v212, v212
	v_rcp_f32_e32 v213, v213
	v_rcp_f32_e32 v214, v214
	v_rcp_f32_e32 v215, v215
	v_pk_mul_f32 v[94:95], v[94:95], v[200:201]
	v_pk_mul_f32 v[96:97], v[96:97], v[202:203]
	v_pk_mul_f32 v[90:91], v[90:91], v[204:205]
	v_pk_mul_f32 v[92:93], v[92:93], v[206:207]
	v_pk_mul_f32 v[78:79], v[78:79], v[208:209]
	v_pk_mul_f32 v[80:81], v[80:81], v[210:211]
	v_pk_mul_f32 v[74:75], v[74:75], v[212:213]
	v_pk_mul_f32 v[76:77], v[76:77], v[214:215]
	v_pk_mul_f32 v[200:201], v[54:55], s[74:75] op_sel_hi:[1,0]
	v_pk_mul_f32 v[202:203], v[56:57], s[74:75] op_sel_hi:[1,0]
	v_pk_mul_f32 v[204:205], v[50:51], s[74:75] op_sel_hi:[1,0]
	v_pk_mul_f32 v[206:207], v[52:53], s[74:75] op_sel_hi:[1,0]
	v_pk_mul_f32 v[208:209], v[38:39], s[74:75] op_sel_hi:[1,0]
	v_pk_mul_f32 v[210:211], v[40:41], s[74:75] op_sel_hi:[1,0]
	v_pk_mul_f32 v[212:213], v[34:35], s[74:75] op_sel_hi:[1,0]
	v_pk_mul_f32 v[214:215], v[36:37], s[74:75] op_sel_hi:[1,0]
	v_exp_f32_e32 v200, v200
	v_exp_f32_e32 v201, v201
	v_exp_f32_e32 v202, v202
	v_exp_f32_e32 v203, v203
	v_exp_f32_e32 v204, v204
	v_exp_f32_e32 v205, v205
	v_exp_f32_e32 v206, v206
	v_exp_f32_e32 v207, v207
	v_exp_f32_e32 v208, v208
	v_exp_f32_e32 v209, v209
	v_exp_f32_e32 v210, v210
	v_exp_f32_e32 v211, v211
	v_exp_f32_e32 v212, v212
	v_exp_f32_e32 v213, v213
	v_exp_f32_e32 v214, v214
	v_exp_f32_e32 v215, v215
	v_pk_add_f32 v[200:201], v[200:201], s[88:89] op_sel_hi:[1,0]
	v_pk_add_f32 v[202:203], v[202:203], s[88:89] op_sel_hi:[1,0]
	v_pk_add_f32 v[204:205], v[204:205], s[88:89] op_sel_hi:[1,0]
	v_pk_add_f32 v[206:207], v[206:207], s[88:89] op_sel_hi:[1,0]
	v_pk_add_f32 v[208:209], v[208:209], s[88:89] op_sel_hi:[1,0]
	v_pk_add_f32 v[210:211], v[210:211], s[88:89] op_sel_hi:[1,0]
	v_pk_add_f32 v[212:213], v[212:213], s[88:89] op_sel_hi:[1,0]
	v_pk_add_f32 v[214:215], v[214:215], s[88:89] op_sel_hi:[1,0]
	v_rcp_f32_e32 v200, v200
	v_rcp_f32_e32 v201, v201
	v_rcp_f32_e32 v202, v202
	v_rcp_f32_e32 v203, v203
	v_rcp_f32_e32 v204, v204
	v_rcp_f32_e32 v205, v205
	v_rcp_f32_e32 v206, v206
	v_rcp_f32_e32 v207, v207
	v_rcp_f32_e32 v208, v208
	v_rcp_f32_e32 v209, v209
	v_rcp_f32_e32 v210, v210
	v_rcp_f32_e32 v211, v211
	v_rcp_f32_e32 v212, v212
	v_rcp_f32_e32 v213, v213
	v_rcp_f32_e32 v214, v214
	v_rcp_f32_e32 v215, v215
	v_pk_mul_f32 v[62:63], v[62:63], v[200:201]
	v_pk_mul_f32 v[64:65], v[64:65], v[202:203]
	v_pk_mul_f32 v[58:59], v[58:59], v[204:205]
	v_pk_mul_f32 v[60:61], v[60:61], v[206:207]
	v_pk_mul_f32 v[46:47], v[46:47], v[208:209]
	v_pk_mul_f32 v[48:49], v[48:49], v[210:211]
	v_pk_mul_f32 v[42:43], v[42:43], v[212:213]
	v_pk_mul_f32 v[44:45], v[44:45], v[214:215]
	v_pk_mul_f32 v[200:201], v[22:23], s[74:75] op_sel_hi:[1,0]
	v_pk_mul_f32 v[202:203], v[24:25], s[74:75] op_sel_hi:[1,0]
	v_pk_mul_f32 v[204:205], v[18:19], s[74:75] op_sel_hi:[1,0]
	v_pk_mul_f32 v[206:207], v[20:21], s[74:75] op_sel_hi:[1,0]
	v_pk_mul_f32 v[208:209], v[6:7], s[74:75] op_sel_hi:[1,0]
	v_pk_mul_f32 v[210:211], v[8:9], s[74:75] op_sel_hi:[1,0]
	v_pk_mul_f32 v[212:213], v[2:3], s[74:75] op_sel_hi:[1,0]
	v_pk_mul_f32 v[214:215], v[4:5], s[74:75] op_sel_hi:[1,0]
	v_exp_f32_e32 v200, v200
	v_exp_f32_e32 v201, v201
	v_exp_f32_e32 v202, v202
	v_exp_f32_e32 v203, v203
	v_exp_f32_e32 v204, v204
	v_exp_f32_e32 v205, v205
	v_exp_f32_e32 v206, v206
	v_exp_f32_e32 v207, v207
	v_exp_f32_e32 v208, v208
	v_exp_f32_e32 v209, v209
	v_exp_f32_e32 v210, v210
	v_exp_f32_e32 v211, v211
	v_exp_f32_e32 v212, v212
	v_exp_f32_e32 v213, v213
	v_exp_f32_e32 v214, v214
	v_exp_f32_e32 v215, v215
	v_pk_add_f32 v[200:201], v[200:201], s[88:89] op_sel_hi:[1,0]
	v_pk_add_f32 v[202:203], v[202:203], s[88:89] op_sel_hi:[1,0]
	v_pk_add_f32 v[204:205], v[204:205], s[88:89] op_sel_hi:[1,0]
	v_pk_add_f32 v[206:207], v[206:207], s[88:89] op_sel_hi:[1,0]
	v_pk_add_f32 v[208:209], v[208:209], s[88:89] op_sel_hi:[1,0]
	v_pk_add_f32 v[210:211], v[210:211], s[88:89] op_sel_hi:[1,0]
	v_pk_add_f32 v[212:213], v[212:213], s[88:89] op_sel_hi:[1,0]
	v_pk_add_f32 v[214:215], v[214:215], s[88:89] op_sel_hi:[1,0]
	v_rcp_f32_e32 v200, v200
	v_rcp_f32_e32 v201, v201
	v_rcp_f32_e32 v202, v202
	v_rcp_f32_e32 v203, v203
	v_rcp_f32_e32 v204, v204
	v_rcp_f32_e32 v205, v205
	v_rcp_f32_e32 v206, v206
	v_rcp_f32_e32 v207, v207
	v_rcp_f32_e32 v208, v208
	v_rcp_f32_e32 v209, v209
	v_rcp_f32_e32 v210, v210
	v_rcp_f32_e32 v211, v211
	v_rcp_f32_e32 v212, v212
	v_rcp_f32_e32 v213, v213
	v_rcp_f32_e32 v214, v214
	v_rcp_f32_e32 v215, v215
	v_pk_mul_f32 v[30:31], v[30:31], v[200:201]
	v_pk_mul_f32 v[32:33], v[32:33], v[202:203]
	v_pk_mul_f32 v[26:27], v[26:27], v[204:205]
	v_pk_mul_f32 v[28:29], v[28:29], v[206:207]
	v_pk_mul_f32 v[14:15], v[14:15], v[208:209]
	v_pk_mul_f32 v[16:17], v[16:17], v[210:211]
	v_pk_mul_f32 v[10:11], v[10:11], v[212:213]
	v_pk_mul_f32 v[12:13], v[12:13], v[214:215]
	s_mov_b64 s[56:57], 0x8000
	s_mov_b64 s[38:39], 0x28000
	s_waitcnt vmcnt(7)
	v_lshlrev_b32_e32 v184, 16, v130
	v_and_b32_e32 v185, 0xffff0000, v130
	v_lshlrev_b32_e32 v186, 16, v131
	v_and_b32_e32 v187, 0xffff0000, v131
	v_lshlrev_b32_e32 v188, 16, v132
	v_and_b32_e32 v189, 0xffff0000, v132
	v_lshlrev_b32_e32 v190, 16, v133
	v_and_b32_e32 v191, 0xffff0000, v133
	v_pk_mul_f32 v[126:127], v[126:127], v[184:185]
	v_pk_mul_f32 v[128:129], v[128:129], v[186:187]
	v_pk_mul_f32 v[122:123], v[122:123], v[188:189]
	v_pk_mul_f32 v[124:125], v[124:125], v[190:191]
	v_cvt_pk_bf16_f32 v244, v126, v127
	v_cvt_pk_bf16_f32 v245, v128, v129
	v_cvt_pk_bf16_f32 v246, v122, v123
	v_cvt_pk_bf16_f32 v247, v124, v125
	global_store_dwordx4 v[216:217], v[244:247], off
	v_lshl_add_u64 v[216:217], v[216:217], 0, s[56:57]
	s_waitcnt vmcnt(7)
	v_lshlrev_b32_e32 v218, 16, v134
	v_and_b32_e32 v219, 0xffff0000, v134
	v_lshlrev_b32_e32 v220, 16, v135
	v_and_b32_e32 v221, 0xffff0000, v135
	v_lshlrev_b32_e32 v222, 16, v136
	v_and_b32_e32 v223, 0xffff0000, v136
	v_lshlrev_b32_e32 v224, 16, v137
	v_and_b32_e32 v225, 0xffff0000, v137
	v_pk_mul_f32 v[110:111], v[110:111], v[218:219]
	v_pk_mul_f32 v[112:113], v[112:113], v[220:221]
	v_pk_mul_f32 v[106:107], v[106:107], v[222:223]
	v_pk_mul_f32 v[108:109], v[108:109], v[224:225]
	v_cvt_pk_bf16_f32 v248, v110, v111
	v_cvt_pk_bf16_f32 v249, v112, v113
	v_cvt_pk_bf16_f32 v250, v106, v107
	v_cvt_pk_bf16_f32 v251, v108, v109
	global_store_dwordx4 v[216:217], v[248:251], off
	v_lshl_add_u64 v[216:217], v[216:217], 0, s[56:57]
	s_waitcnt vmcnt(7)
	v_lshlrev_b32_e32 v184, 16, v138
	v_and_b32_e32 v185, 0xffff0000, v138
	v_lshlrev_b32_e32 v186, 16, v139
	v_and_b32_e32 v187, 0xffff0000, v139
	v_lshlrev_b32_e32 v188, 16, v140
	v_and_b32_e32 v189, 0xffff0000, v140
	v_lshlrev_b32_e32 v190, 16, v141
	v_and_b32_e32 v191, 0xffff0000, v141
	v_pk_mul_f32 v[94:95], v[94:95], v[184:185]
	v_pk_mul_f32 v[96:97], v[96:97], v[186:187]
	v_pk_mul_f32 v[90:91], v[90:91], v[188:189]
	v_pk_mul_f32 v[92:93], v[92:93], v[190:191]
	v_cvt_pk_bf16_f32 v244, v94, v95
	v_cvt_pk_bf16_f32 v245, v96, v97
	v_cvt_pk_bf16_f32 v246, v90, v91
	v_cvt_pk_bf16_f32 v247, v92, v93
	global_store_dwordx4 v[216:217], v[244:247], off
	v_lshl_add_u64 v[216:217], v[216:217], 0, s[56:57]
	s_waitcnt vmcnt(7)
	v_lshlrev_b32_e32 v218, 16, v142
	v_and_b32_e32 v219, 0xffff0000, v142
	v_lshlrev_b32_e32 v220, 16, v143
	v_and_b32_e32 v221, 0xffff0000, v143
	v_lshlrev_b32_e32 v222, 16, v144
	v_and_b32_e32 v223, 0xffff0000, v144
	v_lshlrev_b32_e32 v224, 16, v145
	v_and_b32_e32 v225, 0xffff0000, v145
	v_pk_mul_f32 v[78:79], v[78:79], v[218:219]
	v_pk_mul_f32 v[80:81], v[80:81], v[220:221]
	v_pk_mul_f32 v[74:75], v[74:75], v[222:223]
	v_pk_mul_f32 v[76:77], v[76:77], v[224:225]
	v_cvt_pk_bf16_f32 v248, v78, v79
	v_cvt_pk_bf16_f32 v249, v80, v81
	v_cvt_pk_bf16_f32 v250, v74, v75
	v_cvt_pk_bf16_f32 v251, v76, v77
	global_store_dwordx4 v[216:217], v[248:251], off
	v_lshl_add_u64 v[216:217], v[216:217], 0, s[38:39]
	s_waitcnt vmcnt(7)
	v_lshlrev_b32_e32 v184, 16, v146
	v_and_b32_e32 v185, 0xffff0000, v146
	v_lshlrev_b32_e32 v186, 16, v147
	v_and_b32_e32 v187, 0xffff0000, v147
	v_lshlrev_b32_e32 v188, 16, v148
	v_and_b32_e32 v189, 0xffff0000, v148
	v_lshlrev_b32_e32 v190, 16, v149
	v_and_b32_e32 v191, 0xffff0000, v149
	v_pk_mul_f32 v[62:63], v[62:63], v[184:185]
	v_pk_mul_f32 v[64:65], v[64:65], v[186:187]
	v_pk_mul_f32 v[58:59], v[58:59], v[188:189]
	v_pk_mul_f32 v[60:61], v[60:61], v[190:191]
	v_cvt_pk_bf16_f32 v244, v62, v63
	v_cvt_pk_bf16_f32 v245, v64, v65
	v_cvt_pk_bf16_f32 v246, v58, v59
	v_cvt_pk_bf16_f32 v247, v60, v61
	global_store_dwordx4 v[216:217], v[244:247], off
	v_lshl_add_u64 v[216:217], v[216:217], 0, s[56:57]
	s_waitcnt vmcnt(7)
	v_lshlrev_b32_e32 v218, 16, v150
	v_and_b32_e32 v219, 0xffff0000, v150
	v_lshlrev_b32_e32 v220, 16, v151
	v_and_b32_e32 v221, 0xffff0000, v151
	v_lshlrev_b32_e32 v222, 16, v152
	v_and_b32_e32 v223, 0xffff0000, v152
	v_lshlrev_b32_e32 v224, 16, v153
	v_and_b32_e32 v225, 0xffff0000, v153
	v_pk_mul_f32 v[46:47], v[46:47], v[218:219]
	v_pk_mul_f32 v[48:49], v[48:49], v[220:221]
	v_pk_mul_f32 v[42:43], v[42:43], v[222:223]
	v_pk_mul_f32 v[44:45], v[44:45], v[224:225]
	v_cvt_pk_bf16_f32 v248, v46, v47
	v_cvt_pk_bf16_f32 v249, v48, v49
	v_cvt_pk_bf16_f32 v250, v42, v43
	v_cvt_pk_bf16_f32 v251, v44, v45
	global_store_dwordx4 v[216:217], v[248:251], off
	v_lshl_add_u64 v[216:217], v[216:217], 0, s[56:57]
	s_waitcnt vmcnt(7)
	v_lshlrev_b32_e32 v184, 16, v154
	v_and_b32_e32 v185, 0xffff0000, v154
	v_lshlrev_b32_e32 v186, 16, v155
	v_and_b32_e32 v187, 0xffff0000, v155
	v_lshlrev_b32_e32 v188, 16, v156
	v_and_b32_e32 v189, 0xffff0000, v156
	v_lshlrev_b32_e32 v190, 16, v157
	v_and_b32_e32 v191, 0xffff0000, v157
	v_pk_mul_f32 v[30:31], v[30:31], v[184:185]
	v_pk_mul_f32 v[32:33], v[32:33], v[186:187]
	v_pk_mul_f32 v[26:27], v[26:27], v[188:189]
	v_pk_mul_f32 v[28:29], v[28:29], v[190:191]
	v_cvt_pk_bf16_f32 v244, v30, v31
	v_cvt_pk_bf16_f32 v245, v32, v33
	v_cvt_pk_bf16_f32 v246, v26, v27
	v_cvt_pk_bf16_f32 v247, v28, v29
	global_store_dwordx4 v[216:217], v[244:247], off
	v_lshl_add_u64 v[216:217], v[216:217], 0, s[56:57]
	s_waitcnt vmcnt(7)
	v_lshlrev_b32_e32 v218, 16, v158
	v_and_b32_e32 v219, 0xffff0000, v158
	v_lshlrev_b32_e32 v220, 16, v159
	v_and_b32_e32 v221, 0xffff0000, v159
	v_lshlrev_b32_e32 v222, 16, v160
	v_and_b32_e32 v223, 0xffff0000, v160
	v_lshlrev_b32_e32 v224, 16, v161
	v_and_b32_e32 v225, 0xffff0000, v161
	v_pk_mul_f32 v[14:15], v[14:15], v[218:219]
	v_pk_mul_f32 v[16:17], v[16:17], v[220:221]
	v_pk_mul_f32 v[10:11], v[10:11], v[222:223]
	v_pk_mul_f32 v[12:13], v[12:13], v[224:225]
	v_cvt_pk_bf16_f32 v248, v14, v15
	v_cvt_pk_bf16_f32 v249, v16, v17
	v_cvt_pk_bf16_f32 v250, v10, v11
	v_cvt_pk_bf16_f32 v251, v12, v13
	global_store_dwordx4 v[216:217], v[248:251], off
	s_branch .LBB0_221
